# prefill attention: NEG-constant fills (24 v_mov per tile) moved off the common path onto the meta-tile branch, on top of v50
# baseline (speedup 1.0000x reference)
.LBB0_936:
	s_nop 0
	v_cndmask_b32_e64 v180, 0, 1, s[2:3]
	v_add_u32_e32 v233, s54, v196
	s_andn2_b64 vcc, exec, s[12:13]
	v_cmp_ne_u32_e64 s[12:13], 1, v180
	s_cbranch_vccnz .Lpf_neg_a
	s_and_b64 vcc, exec, s[12:13]
	s_cbranch_vccnz .LBB0_939
	v_mov_b32_e32 v156, s68
	v_cmp_gt_i32_e32 vcc, v233, v210
	s_nop 1
	v_cndmask_b32_e32 v1, v152, v156, vcc
	v_cmp_lt_i32_e32 vcc, v233, v210
	s_nop 1
	v_cndmask_b32_e32 v152, v1, v152, vcc
	v_add_u32_e32 v1, 2, v233
	v_cndmask_b32_e32 v153, v225, v153, vcc
	v_cmp_le_i32_e32 vcc, v1, v210
	v_add_u32_e32 v1, 3, v233
	s_nop 0
	v_cndmask_b32_e32 v154, v225, v154, vcc
	v_cmp_le_i32_e32 vcc, v1, v210
	v_add_u32_e32 v1, 16, v233
	s_nop 0
	v_cndmask_b32_e32 v155, v225, v155, vcc
	v_cmp_gt_i32_e32 vcc, v1, v210
	v_add_u32_e32 v1, 17, v233
	s_nop 0
	v_cndmask_b32_e32 v238, v160, v156, vcc
	v_cmp_le_i32_e32 vcc, v1, v210
	v_add_u32_e32 v1, 18, v233
	s_nop 0
	v_cndmask_b32_e32 v239, v225, v161, vcc
	v_cmp_le_i32_e32 vcc, v1, v210
	v_add_u32_e32 v1, 19, v233
	s_nop 0
	v_cndmask_b32_e32 v240, v225, v162, vcc
	v_cmp_le_i32_e32 vcc, v1, v210
	v_add_u32_e32 v1, 32, v233
	s_nop 0
	v_cndmask_b32_e32 v241, v225, v163, vcc
	v_cmp_gt_i32_e32 vcc, v1, v210
	v_add_u32_e32 v1, 33, v233
	s_nop 0
	v_cndmask_b32_e32 v244, v164, v156, vcc
	v_cmp_le_i32_e32 vcc, v1, v210
	v_add_u32_e32 v1, 34, v233
	s_nop 0
	v_cndmask_b32_e32 v245, v225, v165, vcc
	v_cmp_le_i32_e32 vcc, v1, v210
	v_add_u32_e32 v1, 35, v233
	s_nop 0
	v_cndmask_b32_e32 v246, v225, v166, vcc
	v_cmp_le_i32_e32 vcc, v1, v210
	v_add_u32_e32 v1, 48, v233
	s_nop 0
	v_cndmask_b32_e32 v247, v225, v167, vcc
	v_cmp_gt_i32_e32 vcc, v1, v210
	s_nop 1
	v_cndmask_b32_e32 v1, v168, v156, vcc
	v_add_u32_e32 v156, 49, v233
	v_cmp_le_i32_e32 vcc, v156, v210
	v_add_u32_e32 v156, 50, v233
	s_nop 0
	v_cndmask_b32_e32 v242, v225, v169, vcc
	v_cmp_le_i32_e32 vcc, v156, v210
	v_add_u32_e32 v156, 51, v233
	s_nop 0
	v_cndmask_b32_e32 v243, v225, v170, vcc
	v_cmp_le_i32_e32 vcc, v156, v210
	s_nop 1
	v_cndmask_b32_e32 v232, v225, v171, vcc
	s_branch .LBB0_940
.Lpf_neg_a:
	v_mov_b32_e32 v1, 0xf149f2ca
	v_mov_b32_e32 v242, 0xf149f2ca
	v_mov_b32_e32 v243, 0xf149f2ca
	v_mov_b32_e32 v232, 0xf149f2ca
	v_mov_b32_e32 v244, 0xf149f2ca
	v_mov_b32_e32 v245, 0xf149f2ca
	v_mov_b32_e32 v246, 0xf149f2ca
	v_mov_b32_e32 v247, 0xf149f2ca
	v_mov_b32_e32 v238, 0xf149f2ca
	v_mov_b32_e32 v239, 0xf149f2ca
	v_mov_b32_e32 v240, 0xf149f2ca
	v_mov_b32_e32 v241, 0xf149f2ca
	s_branch .LBB0_941

.LBB0_945:
	s_andn2_b64 vcc, exec, s[0:1]
	s_cbranch_vccnz .Lpf_neg_b
	s_and_b64 vcc, exec, s[12:13]
	s_cbranch_vccnz .LBB0_948
	v_mov_b32_e32 v152, s68
	v_cmp_gt_i32_e32 vcc, v233, v213
	s_nop 1
	v_cndmask_b32_e32 v152, v136, v152, vcc
	v_cmp_lt_i32_e32 vcc, v233, v213
	s_nop 1
	v_cndmask_b32_e32 v136, v152, v136, vcc
	v_cndmask_b32_e32 v137, v225, v137, vcc
	v_cmp_le_i32_e32 vcc, v233, v214
	v_mov_b32_e32 v152, s68
	s_nop 0
	v_cndmask_b32_e32 v138, v225, v138, vcc
	v_cmp_le_i32_e32 vcc, v233, v215
	s_nop 1
	v_cndmask_b32_e32 v139, v225, v139, vcc
	v_cmp_gt_i32_e32 vcc, v233, v210
	s_nop 1
	v_cndmask_b32_e32 v152, v140, v152, vcc
	v_cmp_lt_i32_e32 vcc, v233, v210
	s_nop 1
	v_cndmask_b32_e32 v245, v152, v140, vcc
	v_add_u32_e32 v140, 2, v233
	v_cndmask_b32_e32 v244, v225, v141, vcc
	v_cmp_le_i32_e32 vcc, v140, v210
	v_add_u32_e32 v140, 3, v233
	v_add_u32_e32 v141, 16, v233
	v_cndmask_b32_e32 v243, v225, v142, vcc
	v_cmp_le_i32_e32 vcc, v140, v210
	v_mov_b32_e32 v140, s68
	s_nop 0
	v_cndmask_b32_e32 v242, v225, v143, vcc
	v_cmp_gt_i32_e32 vcc, v141, v210
	v_add_u32_e32 v141, 32, v233
	s_nop 0
	v_cndmask_b32_e32 v232, v144, v140, vcc
	v_add_u32_e32 v140, 17, v233
	v_cmp_le_i32_e32 vcc, v140, v210
	v_add_u32_e32 v140, 18, v233
	s_nop 0
	v_cndmask_b32_e32 v170, v225, v145, vcc
	v_cmp_le_i32_e32 vcc, v140, v210
	v_add_u32_e32 v140, 19, v233
	s_nop 0
	v_cndmask_b32_e32 v171, v225, v146, vcc
	v_cmp_le_i32_e32 vcc, v140, v210
	v_mov_b32_e32 v140, s68
	s_nop 0
	v_cndmask_b32_e32 v169, v225, v147, vcc
	v_cmp_gt_i32_e32 vcc, v141, v210
	s_nop 1
	v_cndmask_b32_e32 v167, v148, v140, vcc
	v_add_u32_e32 v140, 33, v233
	v_cmp_le_i32_e32 vcc, v140, v210
	v_add_u32_e32 v140, 34, v233
	s_nop 0
	v_cndmask_b32_e32 v168, v225, v149, vcc
	v_cmp_le_i32_e32 vcc, v140, v210
	v_add_u32_e32 v140, 35, v233
	s_nop 0
	v_cndmask_b32_e32 v166, v225, v150, vcc
	v_cmp_le_i32_e32 vcc, v140, v210
	s_nop 1
	v_cndmask_b32_e32 v165, v225, v151, vcc
	s_branch .LBB0_949
.Lpf_neg_b:
	v_mov_b32_e32 v167, 0xf149f2ca
	v_mov_b32_e32 v168, 0xf149f2ca
	v_mov_b32_e32 v166, 0xf149f2ca
	v_mov_b32_e32 v165, 0xf149f2ca
	v_mov_b32_e32 v232, 0xf149f2ca
	v_mov_b32_e32 v170, 0xf149f2ca
	v_mov_b32_e32 v171, 0xf149f2ca
	v_mov_b32_e32 v169, 0xf149f2ca
	v_mov_b32_e32 v245, 0xf149f2ca
	v_mov_b32_e32 v244, 0xf149f2ca
	v_mov_b32_e32 v243, 0xf149f2ca
	v_mov_b32_e32 v242, 0xf149f2ca
	s_branch .LBB0_950
